# v014 with w_gate_up rows interleaved in blocks of two (g,g,u,u) in P0 so the P8 SwiGLU epilogue uses packed f32 ops on register pairs (377 instead of 505 instructions)
# speedup vs baseline: 1.0071x; 1.0011x over previous
.LBB0_31:
	s_andn2_b64 vcc, exec, s[14:15]
	s_cbranch_vccnz .LBB0_35
	s_add_i32 s12, s22, 0xea00
	s_and_b32 s14, s12, 0xffff
	s_mul_i32 s14, s14, 0xba2f
	s_lshr_b32 s14, s14, 23
	s_mul_i32 s15, s14, 0xb0
	s_sub_i32 s15, s12, s15
	s_lshl_b32 s12, s14, 6
	s_lshl_b32 s14, s15, 5
	s_and_b32 s14, s14, 0xffe0
	v_or_b32_e32 v0, s14, v178
	v_and_b32_e32 v22, 2, v0
	v_mul_u32_u24_e32 v22, 0x580, v22
	v_lshrrev_b32_e32 v23, 1, v0
	v_and_b32_e32 v23, -2, v23
	v_and_b32_e32 v0, 1, v0
	v_add3_u32 v0, v0, v23, v22
	v_or_b32_e32 v54, s12, v56
	v_lshlrev_b32_e32 v0, 2, v0
	v_lshl_add_u64 v[46:47], s[42:43], 0, v[0:1]
	v_or_b32_e32 v0, 2, v54
	v_mad_u64_u32 v[24:25], s[24:25], v0, s19, v[46:47]
	v_or_b32_e32 v0, 4, v54
	v_mad_u64_u32 v[26:27], s[24:25], v0, s19, v[46:47]
	v_or_b32_e32 v0, 6, v54
	v_mad_u64_u32 v[28:29], s[24:25], v0, s19, v[46:47]
	v_or_b32_e32 v0, 8, v54
	v_mad_u64_u32 v[30:31], s[24:25], v0, s19, v[46:47]
	v_or_b32_e32 v0, 10, v54
	v_mad_u64_u32 v[32:33], s[24:25], v0, s19, v[46:47]
	v_or_b32_e32 v0, 12, v54
	v_mad_u64_u32 v[34:35], s[24:25], v0, s19, v[46:47]
	v_or_b32_e32 v0, 14, v54
	v_mad_u64_u32 v[22:23], s[24:25], v54, s19, v[46:47]
	v_mad_u64_u32 v[36:37], s[24:25], v0, s19, v[46:47]
	v_or_b32_e32 v0, 16, v54
	global_load_dword v22, v[22:23], off nt
	s_nop 0
	global_load_dword v23, v[24:25], off nt
	s_nop 0
	global_load_dword v24, v[26:27], off nt
	global_load_dword v25, v[28:29], off nt
	s_nop 0
	global_load_dword v26, v[30:31], off nt
	global_load_dword v27, v[32:33], off nt
	global_load_dword v28, v[34:35], off nt
	global_load_dword v29, v[36:37], off nt
	v_mad_u64_u32 v[30:31], s[24:25], v0, s19, v[46:47]
	v_or_b32_e32 v0, 18, v54
	v_mad_u64_u32 v[32:33], s[24:25], v0, s19, v[46:47]
	v_or_b32_e32 v0, 20, v54
	v_mad_u64_u32 v[34:35], s[24:25], v0, s19, v[46:47]
	v_or_b32_e32 v0, 22, v54
	v_mad_u64_u32 v[36:37], s[24:25], v0, s19, v[46:47]
	v_or_b32_e32 v0, 24, v54
	v_mad_u64_u32 v[38:39], s[24:25], v0, s19, v[46:47]
	v_or_b32_e32 v0, 26, v54
	v_mad_u64_u32 v[40:41], s[24:25], v0, s19, v[46:47]
	v_or_b32_e32 v0, 28, v54
	v_mad_u64_u32 v[42:43], s[24:25], v0, s19, v[46:47]
	v_or_b32_e32 v0, 30, v54
	v_mad_u64_u32 v[44:45], s[24:25], v0, s19, v[46:47]
	v_or_b32_e32 v0, 32, v54
	global_load_dword v30, v[30:31], off nt
	s_nop 0
	global_load_dword v31, v[32:33], off nt
	s_nop 0
	global_load_dword v32, v[34:35], off nt
	global_load_dword v33, v[36:37], off nt
	s_nop 0
	global_load_dword v34, v[38:39], off nt
	global_load_dword v35, v[40:41], off nt
	global_load_dword v36, v[42:43], off nt
	global_load_dword v37, v[44:45], off nt
	v_mad_u64_u32 v[38:39], s[24:25], v0, s19, v[46:47]
	v_or_b32_e32 v0, 34, v54
	v_mad_u64_u32 v[40:41], s[24:25], v0, s19, v[46:47]
	v_or_b32_e32 v0, 36, v54
	v_mad_u64_u32 v[42:43], s[24:25], v0, s19, v[46:47]
	v_or_b32_e32 v0, 38, v54
	v_mad_u64_u32 v[44:45], s[24:25], v0, s19, v[46:47]
	v_or_b32_e32 v0, 40, v54
	v_mad_u64_u32 v[48:49], s[24:25], v0, s19, v[46:47]
	v_or_b32_e32 v0, 42, v54
	v_mad_u64_u32 v[50:51], s[24:25], v0, s19, v[46:47]
	v_or_b32_e32 v0, 44, v54
	v_mad_u64_u32 v[52:53], s[24:25], v0, s19, v[46:47]
	v_or_b32_e32 v0, 46, v54
	v_mad_u64_u32 v[72:73], s[24:25], v0, s19, v[46:47]
	v_or_b32_e32 v0, 48, v54
	global_load_dword v38, v[38:39], off nt
	s_nop 0
	global_load_dword v39, v[40:41], off nt
	s_nop 0
	global_load_dword v40, v[42:43], off nt
	global_load_dword v41, v[44:45], off nt
	s_nop 0
	global_load_dword v42, v[48:49], off nt
	global_load_dword v43, v[50:51], off nt
	global_load_dword v44, v[52:53], off nt
	global_load_dword v45, v[72:73], off nt
	v_mad_u64_u32 v[48:49], s[24:25], v0, s19, v[46:47]
	v_or_b32_e32 v0, 50, v54
	v_mad_u64_u32 v[50:51], s[24:25], v0, s19, v[46:47]
	v_or_b32_e32 v0, 52, v54
	v_mad_u64_u32 v[52:53], s[24:25], v0, s19, v[46:47]
	v_or_b32_e32 v0, 54, v54
	v_mad_u64_u32 v[72:73], s[24:25], v0, s19, v[46:47]
	v_or_b32_e32 v0, 56, v54
	v_mad_u64_u32 v[74:75], s[24:25], v0, s19, v[46:47]
	v_or_b32_e32 v0, 58, v54
	v_mad_u64_u32 v[76:77], s[24:25], v0, s19, v[46:47]
	v_or_b32_e32 v0, 60, v54
	v_mad_u64_u32 v[78:79], s[24:25], v0, s19, v[46:47]
	v_or_b32_e32 v0, 62, v54
	v_mad_u64_u32 v[80:81], s[24:25], v0, s19, v[46:47]
	global_load_dword v46, v[48:49], off nt
	global_load_dword v47, v[50:51], off nt
	s_nop 0
	global_load_dword v48, v[52:53], off nt
	global_load_dword v49, v[72:73], off nt
	s_nop 0
	global_load_dword v52, v[74:75], off nt
	global_load_dword v53, v[76:77], off nt
	global_load_dword v50, v[78:79], off nt
	global_load_dword v51, v[80:81], off nt
	s_andn2_b64 vcc, exec, s[0:1]
	s_cbranch_vccnz .LBB0_34
	v_lshlrev_b32_e32 v0, 2, v54
	global_load_dword v54, v0, s[40:41]
	global_load_dword v55, v0, s[40:41] offset:8
	global_load_dword v72, v0, s[40:41] offset:16
	global_load_dword v73, v0, s[40:41] offset:24
	global_load_dword v74, v0, s[40:41] offset:32
	global_load_dword v75, v0, s[40:41] offset:40
	global_load_dword v76, v0, s[40:41] offset:48
	global_load_dword v77, v0, s[40:41] offset:56
	global_load_dword v78, v0, s[40:41] offset:64
	global_load_dword v79, v0, s[40:41] offset:72
	global_load_dword v80, v0, s[40:41] offset:80
	global_load_dword v81, v0, s[40:41] offset:88
	global_load_dword v82, v0, s[40:41] offset:96
	global_load_dword v83, v0, s[40:41] offset:104
	global_load_dword v84, v0, s[40:41] offset:112
	global_load_dword v85, v0, s[40:41] offset:120
	global_load_dword v86, v0, s[40:41] offset:128
	global_load_dword v87, v0, s[40:41] offset:136
	global_load_dword v88, v0, s[40:41] offset:144
	global_load_dword v89, v0, s[40:41] offset:152
	global_load_dword v90, v0, s[40:41] offset:160
	global_load_dword v91, v0, s[40:41] offset:168
	global_load_dword v92, v0, s[40:41] offset:176
	global_load_dword v93, v0, s[40:41] offset:184
	global_load_dword v94, v0, s[40:41] offset:192
	global_load_dword v95, v0, s[40:41] offset:200
	global_load_dword v96, v0, s[40:41] offset:208
	global_load_dword v97, v0, s[40:41] offset:216
	global_load_dword v98, v0, s[40:41] offset:224
	global_load_dword v99, v0, s[40:41] offset:232
	global_load_dword v100, v0, s[40:41] offset:240
	global_load_dword v101, v0, s[40:41] offset:248
	s_waitcnt vmcnt(30)
	v_pk_mul_f32 v[22:23], v[22:23], v[54:55]
	s_waitcnt vmcnt(28)
	v_pk_mul_f32 v[24:25], v[24:25], v[72:73]
	s_waitcnt vmcnt(26)
	v_pk_mul_f32 v[26:27], v[26:27], v[74:75]
	s_waitcnt vmcnt(24)
	v_pk_mul_f32 v[28:29], v[28:29], v[76:77]
	s_waitcnt vmcnt(22)
	v_pk_mul_f32 v[30:31], v[30:31], v[78:79]
	s_waitcnt vmcnt(20)
	v_pk_mul_f32 v[32:33], v[32:33], v[80:81]
	s_waitcnt vmcnt(18)
	v_pk_mul_f32 v[34:35], v[34:35], v[82:83]
	s_waitcnt vmcnt(16)
	v_pk_mul_f32 v[36:37], v[36:37], v[84:85]
	s_waitcnt vmcnt(14)
	v_pk_mul_f32 v[38:39], v[38:39], v[86:87]
	s_waitcnt vmcnt(12)
	v_pk_mul_f32 v[40:41], v[40:41], v[88:89]
	s_waitcnt vmcnt(10)
	v_pk_mul_f32 v[42:43], v[42:43], v[90:91]
	s_waitcnt vmcnt(8)
	v_pk_mul_f32 v[44:45], v[44:45], v[92:93]
	s_waitcnt vmcnt(6)
	v_pk_mul_f32 v[46:47], v[46:47], v[94:95]
	s_waitcnt vmcnt(4)
	v_pk_mul_f32 v[48:49], v[48:49], v[96:97]
	s_waitcnt vmcnt(2)
	v_pk_mul_f32 v[52:53], v[52:53], v[98:99]
	s_waitcnt vmcnt(0)
	v_pk_mul_f32 v[50:51], v[50:51], v[100:101]

.LBB0_893:
	v_lshl_add_u32 v146, s26, 8, v154
	v_ashrrev_i32_e32 v147, 31, v146
	v_lshl_add_u64 v[144:145], v[146:147], 2, s[12:13]
	global_load_dword v170, v[144:145], off
	global_load_dword v171, v[144:145], off offset:64
	global_load_dword v172, v[144:145], off offset:128
	global_load_dword v173, v[144:145], off offset:192
	global_load_dword v174, v[144:145], off offset:512
	global_load_dword v175, v[144:145], off offset:576
	global_load_dword v176, v[144:145], off offset:640
	global_load_dword v177, v[144:145], off offset:704
	v_pk_mul_f32 v[126:127], v[124:125], v[126:127]
	v_pk_mul_f32 v[122:123], v[120:121], v[122:123]
	v_pk_mul_f32 v[118:119], v[116:117], v[118:119]
	v_pk_mul_f32 v[114:115], v[112:113], v[114:115]
	v_pk_mul_f32 v[110:111], v[108:109], v[110:111]
	v_pk_mul_f32 v[106:107], v[104:105], v[106:107]
	v_pk_mul_f32 v[102:103], v[100:101], v[102:103]
	v_pk_mul_f32 v[98:99], v[96:97], v[98:99]
	v_pk_mul_f32 v[94:95], v[92:93], v[94:95]
	v_pk_mul_f32 v[90:91], v[88:89], v[90:91]
	v_pk_mul_f32 v[86:87], v[84:85], v[86:87]
	v_pk_mul_f32 v[82:83], v[80:81], v[82:83]
	v_pk_mul_f32 v[78:79], v[76:77], v[78:79]
	v_pk_mul_f32 v[74:75], v[72:73], v[74:75]
	v_pk_mul_f32 v[70:71], v[68:69], v[70:71]
	v_pk_mul_f32 v[66:67], v[64:65], v[66:67]
	v_pk_mul_f32 v[62:63], v[60:61], v[62:63]
	v_pk_mul_f32 v[58:59], v[56:57], v[58:59]
	v_pk_mul_f32 v[54:55], v[52:53], v[54:55]
	v_pk_mul_f32 v[50:51], v[48:49], v[50:51]
	v_pk_mul_f32 v[46:47], v[44:45], v[46:47]
	v_pk_mul_f32 v[42:43], v[40:41], v[42:43]
	v_pk_mul_f32 v[38:39], v[36:37], v[38:39]
	v_pk_mul_f32 v[34:35], v[32:33], v[34:35]
	v_pk_mul_f32 v[30:31], v[28:29], v[30:31]
	v_pk_mul_f32 v[26:27], v[24:25], v[26:27]
	v_pk_mul_f32 v[22:23], v[20:21], v[22:23]
	v_pk_mul_f32 v[18:19], v[16:17], v[18:19]
	v_pk_mul_f32 v[14:15], v[12:13], v[14:15]
	v_pk_mul_f32 v[10:11], v[8:9], v[10:11]
	v_pk_mul_f32 v[6:7], v[4:5], v[6:7]
	v_pk_mul_f32 v[2:3], v[0:1], v[2:3]
	s_waitcnt vmcnt(0)
	v_lshl_or_b32 v147, s55, 8, v156
	v_mov_b64_e32 v[144:145], s[10:11]
	v_mad_i64_i32 v[166:167], s[28:29], v146, s54, v[144:145]
	v_ashrrev_i32_e32 v146, 1, v147
	v_ashrrev_i32_e32 v147, 31, v146
	v_lshlrev_b64 v[146:147], 1, v[146:147]
	v_lshl_add_u64 v[166:167], v[166:167], 0, v[146:147]
	v_lshrrev_b32_e32 v165, 4, v214
	v_and_b32_e32 v165, 1, v165
	v_mul_u32_u24_e32 v168, 0x15ff8, v165
	v_mov_b32_e32 v169, 0
	v_lshl_add_u64 v[168:169], v[166:167], 0, v[168:169]
	s_mov_b64 s[64:65], 0x2c000
	s_mov_b64 s[66:67], 0x84000
	s_andn2_b64 vcc, exec, s[2:3]
	s_mov_b64 s[2:3], -1
	v_fmamk_f32 v164, v170, 0x3a800000, v160
	v_rsq_f32_e32 v163, v164
	s_nop 0
	v_mul_f32_e32 v163, 0xbfb8aa3b, v163
	v_pk_mul_f32 v[144:145], v[124:125], v[162:163] op_sel:[0,1] op_sel_hi:[1,1]
	v_pk_mul_f32 v[146:147], v[120:121], v[162:163] op_sel:[0,1] op_sel_hi:[1,1]
	v_exp_f32_e32 v144, v144
	v_exp_f32_e32 v145, v145
	v_exp_f32_e32 v146, v146
	v_exp_f32_e32 v147, v147
	v_pk_fma_f32 v[144:145], v[144:145], v[164:165], v[164:165] op_sel_hi:[1,0,0]
	v_pk_fma_f32 v[146:147], v[146:147], v[164:165], v[164:165] op_sel_hi:[1,0,0]
	v_rcp_f32_e32 v144, v144
	v_rcp_f32_e32 v145, v145
	v_rcp_f32_e32 v146, v146
	v_rcp_f32_e32 v147, v147
	v_pk_mul_f32 v[126:127], v[126:127], v[144:145]
	v_pk_mul_f32 v[122:123], v[122:123], v[146:147]
	v_cvt_pk_bf16_f32 v186, v126, v127
	v_cvt_pk_bf16_f32 v187, v122, v123
	v_pk_mul_f32 v[178:179], v[116:117], v[162:163] op_sel:[0,1] op_sel_hi:[1,1]
	v_pk_mul_f32 v[180:181], v[112:113], v[162:163] op_sel:[0,1] op_sel_hi:[1,1]
	v_exp_f32_e32 v178, v178
	v_exp_f32_e32 v179, v179
	v_exp_f32_e32 v180, v180
	v_exp_f32_e32 v181, v181
	v_pk_fma_f32 v[178:179], v[178:179], v[164:165], v[164:165] op_sel_hi:[1,0,0]
	v_pk_fma_f32 v[180:181], v[180:181], v[164:165], v[164:165] op_sel_hi:[1,0,0]
	v_rcp_f32_e32 v178, v178
	v_rcp_f32_e32 v179, v179
	v_rcp_f32_e32 v180, v180
	v_rcp_f32_e32 v181, v181
	v_pk_mul_f32 v[118:119], v[118:119], v[178:179]
	v_pk_mul_f32 v[114:115], v[114:115], v[180:181]
	v_cvt_pk_bf16_f32 v190, v118, v119
	v_cvt_pk_bf16_f32 v191, v114, v115
	v_fmamk_f32 v164, v171, 0x3a800000, v160
	v_rsq_f32_e32 v163, v164
	s_nop 0
	v_mul_f32_e32 v163, 0xbfb8aa3b, v163
	v_pk_mul_f32 v[144:145], v[108:109], v[162:163] op_sel:[0,1] op_sel_hi:[1,1]
	v_pk_mul_f32 v[146:147], v[104:105], v[162:163] op_sel:[0,1] op_sel_hi:[1,1]
	v_exp_f32_e32 v144, v144
	v_exp_f32_e32 v145, v145
	v_exp_f32_e32 v146, v146
	v_exp_f32_e32 v147, v147
	v_pk_fma_f32 v[144:145], v[144:145], v[164:165], v[164:165] op_sel_hi:[1,0,0]
	v_pk_fma_f32 v[146:147], v[146:147], v[164:165], v[164:165] op_sel_hi:[1,0,0]
	v_rcp_f32_e32 v144, v144
	v_rcp_f32_e32 v145, v145
	v_rcp_f32_e32 v146, v146
	v_rcp_f32_e32 v147, v147
	v_pk_mul_f32 v[110:111], v[110:111], v[144:145]
	v_pk_mul_f32 v[106:107], v[106:107], v[146:147]
	v_cvt_pk_bf16_f32 v188, v110, v111
	v_cvt_pk_bf16_f32 v189, v106, v107
	v_pk_mul_f32 v[178:179], v[100:101], v[162:163] op_sel:[0,1] op_sel_hi:[1,1]
	v_pk_mul_f32 v[180:181], v[96:97], v[162:163] op_sel:[0,1] op_sel_hi:[1,1]
	v_exp_f32_e32 v178, v178
	v_exp_f32_e32 v179, v179
	v_exp_f32_e32 v180, v180
	v_exp_f32_e32 v181, v181
	v_pk_fma_f32 v[178:179], v[178:179], v[164:165], v[164:165] op_sel_hi:[1,0,0]
	v_pk_fma_f32 v[180:181], v[180:181], v[164:165], v[164:165] op_sel_hi:[1,0,0]
	v_rcp_f32_e32 v178, v178
	v_rcp_f32_e32 v179, v179
	v_rcp_f32_e32 v180, v180
	v_rcp_f32_e32 v181, v181
	v_pk_mul_f32 v[102:103], v[102:103], v[178:179]
	v_pk_mul_f32 v[98:99], v[98:99], v[180:181]
	v_cvt_pk_bf16_f32 v192, v102, v103
	v_cvt_pk_bf16_f32 v193, v98, v99
	v_permlane16_swap_b32_e32 v186, v188
	v_permlane16_swap_b32_e32 v187, v189
	global_store_dwordx4 v[168:169], v[186:189], off
	v_permlane16_swap_b32_e32 v190, v192
	v_permlane16_swap_b32_e32 v191, v193
	global_store_dwordx4 v[168:169], v[190:193], off offset:128
	v_fmamk_f32 v164, v172, 0x3a800000, v160
	v_rsq_f32_e32 v163, v164
	s_nop 0
	v_mul_f32_e32 v163, 0xbfb8aa3b, v163
	v_pk_mul_f32 v[144:145], v[92:93], v[162:163] op_sel:[0,1] op_sel_hi:[1,1]
	v_pk_mul_f32 v[146:147], v[88:89], v[162:163] op_sel:[0,1] op_sel_hi:[1,1]
	v_exp_f32_e32 v144, v144
	v_exp_f32_e32 v145, v145
	v_exp_f32_e32 v146, v146
	v_exp_f32_e32 v147, v147
	v_pk_fma_f32 v[144:145], v[144:145], v[164:165], v[164:165] op_sel_hi:[1,0,0]
	v_pk_fma_f32 v[146:147], v[146:147], v[164:165], v[164:165] op_sel_hi:[1,0,0]
	v_rcp_f32_e32 v144, v144
	v_rcp_f32_e32 v145, v145
	v_rcp_f32_e32 v146, v146
	v_rcp_f32_e32 v147, v147
	v_pk_mul_f32 v[94:95], v[94:95], v[144:145]
	v_pk_mul_f32 v[90:91], v[90:91], v[146:147]
	v_cvt_pk_bf16_f32 v194, v94, v95
	v_cvt_pk_bf16_f32 v195, v90, v91
	v_pk_mul_f32 v[178:179], v[84:85], v[162:163] op_sel:[0,1] op_sel_hi:[1,1]
	v_pk_mul_f32 v[180:181], v[80:81], v[162:163] op_sel:[0,1] op_sel_hi:[1,1]
	v_exp_f32_e32 v178, v178
	v_exp_f32_e32 v179, v179
	v_exp_f32_e32 v180, v180
	v_exp_f32_e32 v181, v181
	v_pk_fma_f32 v[178:179], v[178:179], v[164:165], v[164:165] op_sel_hi:[1,0,0]
	v_pk_fma_f32 v[180:181], v[180:181], v[164:165], v[164:165] op_sel_hi:[1,0,0]
	v_rcp_f32_e32 v178, v178
	v_rcp_f32_e32 v179, v179
	v_rcp_f32_e32 v180, v180
	v_rcp_f32_e32 v181, v181
	v_pk_mul_f32 v[86:87], v[86:87], v[178:179]
	v_pk_mul_f32 v[82:83], v[82:83], v[180:181]
	v_cvt_pk_bf16_f32 v198, v86, v87
	v_cvt_pk_bf16_f32 v199, v82, v83
	v_fmamk_f32 v164, v173, 0x3a800000, v160
	v_rsq_f32_e32 v163, v164
	s_nop 0
	v_mul_f32_e32 v163, 0xbfb8aa3b, v163
	v_pk_mul_f32 v[144:145], v[76:77], v[162:163] op_sel:[0,1] op_sel_hi:[1,1]
	v_pk_mul_f32 v[146:147], v[72:73], v[162:163] op_sel:[0,1] op_sel_hi:[1,1]
	v_exp_f32_e32 v144, v144
	v_exp_f32_e32 v145, v145
	v_exp_f32_e32 v146, v146
	v_exp_f32_e32 v147, v147
	v_pk_fma_f32 v[144:145], v[144:145], v[164:165], v[164:165] op_sel_hi:[1,0,0]
	v_pk_fma_f32 v[146:147], v[146:147], v[164:165], v[164:165] op_sel_hi:[1,0,0]
	v_rcp_f32_e32 v144, v144
	v_rcp_f32_e32 v145, v145
	v_rcp_f32_e32 v146, v146
	v_rcp_f32_e32 v147, v147
	v_pk_mul_f32 v[78:79], v[78:79], v[144:145]
	v_pk_mul_f32 v[74:75], v[74:75], v[146:147]
	v_cvt_pk_bf16_f32 v196, v78, v79
	v_cvt_pk_bf16_f32 v197, v74, v75
	v_pk_mul_f32 v[178:179], v[68:69], v[162:163] op_sel:[0,1] op_sel_hi:[1,1]
	v_pk_mul_f32 v[180:181], v[64:65], v[162:163] op_sel:[0,1] op_sel_hi:[1,1]
	v_exp_f32_e32 v178, v178
	v_exp_f32_e32 v179, v179
	v_exp_f32_e32 v180, v180
	v_exp_f32_e32 v181, v181
	v_pk_fma_f32 v[178:179], v[178:179], v[164:165], v[164:165] op_sel_hi:[1,0,0]
	v_pk_fma_f32 v[180:181], v[180:181], v[164:165], v[164:165] op_sel_hi:[1,0,0]
	v_rcp_f32_e32 v178, v178
	v_rcp_f32_e32 v179, v179
	v_rcp_f32_e32 v180, v180
	v_rcp_f32_e32 v181, v181
	v_pk_mul_f32 v[70:71], v[70:71], v[178:179]
	v_pk_mul_f32 v[66:67], v[66:67], v[180:181]
	v_cvt_pk_bf16_f32 v200, v70, v71
	v_cvt_pk_bf16_f32 v201, v66, v67
	v_lshl_add_u64 v[168:169], v[168:169], 0, s[64:65]
	v_permlane16_swap_b32_e32 v194, v196
	v_permlane16_swap_b32_e32 v195, v197
	global_store_dwordx4 v[168:169], v[194:197], off
	v_permlane16_swap_b32_e32 v198, v200
	v_permlane16_swap_b32_e32 v199, v201
	global_store_dwordx4 v[168:169], v[198:201], off offset:128
	v_fmamk_f32 v164, v174, 0x3a800000, v160
	v_rsq_f32_e32 v163, v164
	s_nop 0
	v_mul_f32_e32 v163, 0xbfb8aa3b, v163
	v_pk_mul_f32 v[144:145], v[60:61], v[162:163] op_sel:[0,1] op_sel_hi:[1,1]
	v_pk_mul_f32 v[146:147], v[56:57], v[162:163] op_sel:[0,1] op_sel_hi:[1,1]
	v_exp_f32_e32 v144, v144
	v_exp_f32_e32 v145, v145
	v_exp_f32_e32 v146, v146
	v_exp_f32_e32 v147, v147
	v_pk_fma_f32 v[144:145], v[144:145], v[164:165], v[164:165] op_sel_hi:[1,0,0]
	v_pk_fma_f32 v[146:147], v[146:147], v[164:165], v[164:165] op_sel_hi:[1,0,0]
	v_rcp_f32_e32 v144, v144
	v_rcp_f32_e32 v145, v145
	v_rcp_f32_e32 v146, v146
	v_rcp_f32_e32 v147, v147
	v_pk_mul_f32 v[62:63], v[62:63], v[144:145]
	v_pk_mul_f32 v[58:59], v[58:59], v[146:147]
	v_cvt_pk_bf16_f32 v202, v62, v63
	v_cvt_pk_bf16_f32 v203, v58, v59
	v_pk_mul_f32 v[178:179], v[52:53], v[162:163] op_sel:[0,1] op_sel_hi:[1,1]
	v_pk_mul_f32 v[180:181], v[48:49], v[162:163] op_sel:[0,1] op_sel_hi:[1,1]
	v_exp_f32_e32 v178, v178
	v_exp_f32_e32 v179, v179
	v_exp_f32_e32 v180, v180
	v_exp_f32_e32 v181, v181
	v_pk_fma_f32 v[178:179], v[178:179], v[164:165], v[164:165] op_sel_hi:[1,0,0]
	v_pk_fma_f32 v[180:181], v[180:181], v[164:165], v[164:165] op_sel_hi:[1,0,0]
	v_rcp_f32_e32 v178, v178
	v_rcp_f32_e32 v179, v179
	v_rcp_f32_e32 v180, v180
	v_rcp_f32_e32 v181, v181
	v_pk_mul_f32 v[54:55], v[54:55], v[178:179]
	v_pk_mul_f32 v[50:51], v[50:51], v[180:181]
	v_cvt_pk_bf16_f32 v206, v54, v55
	v_cvt_pk_bf16_f32 v207, v50, v51
	v_fmamk_f32 v164, v175, 0x3a800000, v160
	v_rsq_f32_e32 v163, v164
	s_nop 0
	v_mul_f32_e32 v163, 0xbfb8aa3b, v163
	v_pk_mul_f32 v[144:145], v[44:45], v[162:163] op_sel:[0,1] op_sel_hi:[1,1]
	v_pk_mul_f32 v[146:147], v[40:41], v[162:163] op_sel:[0,1] op_sel_hi:[1,1]
	v_exp_f32_e32 v144, v144
	v_exp_f32_e32 v145, v145
	v_exp_f32_e32 v146, v146
	v_exp_f32_e32 v147, v147
	v_pk_fma_f32 v[144:145], v[144:145], v[164:165], v[164:165] op_sel_hi:[1,0,0]
	v_pk_fma_f32 v[146:147], v[146:147], v[164:165], v[164:165] op_sel_hi:[1,0,0]
	v_rcp_f32_e32 v144, v144
	v_rcp_f32_e32 v145, v145
	v_rcp_f32_e32 v146, v146
	v_rcp_f32_e32 v147, v147
	v_pk_mul_f32 v[46:47], v[46:47], v[144:145]
	v_pk_mul_f32 v[42:43], v[42:43], v[146:147]
	v_cvt_pk_bf16_f32 v204, v46, v47
	v_cvt_pk_bf16_f32 v205, v42, v43
	v_pk_mul_f32 v[178:179], v[36:37], v[162:163] op_sel:[0,1] op_sel_hi:[1,1]
	v_pk_mul_f32 v[180:181], v[32:33], v[162:163] op_sel:[0,1] op_sel_hi:[1,1]
	v_exp_f32_e32 v178, v178
	v_exp_f32_e32 v179, v179
	v_exp_f32_e32 v180, v180
	v_exp_f32_e32 v181, v181
	v_pk_fma_f32 v[178:179], v[178:179], v[164:165], v[164:165] op_sel_hi:[1,0,0]
	v_pk_fma_f32 v[180:181], v[180:181], v[164:165], v[164:165] op_sel_hi:[1,0,0]
	v_rcp_f32_e32 v178, v178
	v_rcp_f32_e32 v179, v179
	v_rcp_f32_e32 v180, v180
	v_rcp_f32_e32 v181, v181
	v_pk_mul_f32 v[38:39], v[38:39], v[178:179]
	v_pk_mul_f32 v[34:35], v[34:35], v[180:181]
	v_cvt_pk_bf16_f32 v208, v38, v39
	v_cvt_pk_bf16_f32 v209, v34, v35
	v_lshl_add_u64 v[168:169], v[168:169], 0, s[66:67]
	v_permlane16_swap_b32_e32 v202, v204
	v_permlane16_swap_b32_e32 v203, v205
	global_store_dwordx4 v[168:169], v[202:205], off
	v_permlane16_swap_b32_e32 v206, v208
	v_permlane16_swap_b32_e32 v207, v209
	global_store_dwordx4 v[168:169], v[206:209], off offset:128
	v_fmamk_f32 v164, v176, 0x3a800000, v160
	v_rsq_f32_e32 v163, v164
	s_nop 0
	v_mul_f32_e32 v163, 0xbfb8aa3b, v163
	v_pk_mul_f32 v[144:145], v[28:29], v[162:163] op_sel:[0,1] op_sel_hi:[1,1]
	v_pk_mul_f32 v[146:147], v[24:25], v[162:163] op_sel:[0,1] op_sel_hi:[1,1]
	v_exp_f32_e32 v144, v144
	v_exp_f32_e32 v145, v145
	v_exp_f32_e32 v146, v146
	v_exp_f32_e32 v147, v147
	v_pk_fma_f32 v[144:145], v[144:145], v[164:165], v[164:165] op_sel_hi:[1,0,0]
	v_pk_fma_f32 v[146:147], v[146:147], v[164:165], v[164:165] op_sel_hi:[1,0,0]
	v_rcp_f32_e32 v144, v144
	v_rcp_f32_e32 v145, v145
	v_rcp_f32_e32 v146, v146
	v_rcp_f32_e32 v147, v147
	v_pk_mul_f32 v[30:31], v[30:31], v[144:145]
	v_pk_mul_f32 v[26:27], v[26:27], v[146:147]
	v_cvt_pk_bf16_f32 v210, v30, v31
	v_cvt_pk_bf16_f32 v211, v26, v27
	v_pk_mul_f32 v[178:179], v[20:21], v[162:163] op_sel:[0,1] op_sel_hi:[1,1]
	v_pk_mul_f32 v[180:181], v[16:17], v[162:163] op_sel:[0,1] op_sel_hi:[1,1]
	v_exp_f32_e32 v178, v178
	v_exp_f32_e32 v179, v179
	v_exp_f32_e32 v180, v180
	v_exp_f32_e32 v181, v181
	v_pk_fma_f32 v[178:179], v[178:179], v[164:165], v[164:165] op_sel_hi:[1,0,0]
	v_pk_fma_f32 v[180:181], v[180:181], v[164:165], v[164:165] op_sel_hi:[1,0,0]
	v_rcp_f32_e32 v178, v178
	v_rcp_f32_e32 v179, v179
	v_rcp_f32_e32 v180, v180
	v_rcp_f32_e32 v181, v181
	v_pk_mul_f32 v[22:23], v[22:23], v[178:179]
	v_pk_mul_f32 v[18:19], v[18:19], v[180:181]
	v_cvt_pk_bf16_f32 v216, v22, v23
	v_cvt_pk_bf16_f32 v217, v18, v19
	v_fmamk_f32 v164, v177, 0x3a800000, v160
	v_rsq_f32_e32 v163, v164
	s_nop 0
	v_mul_f32_e32 v163, 0xbfb8aa3b, v163
	v_pk_mul_f32 v[144:145], v[12:13], v[162:163] op_sel:[0,1] op_sel_hi:[1,1]
	v_pk_mul_f32 v[146:147], v[8:9], v[162:163] op_sel:[0,1] op_sel_hi:[1,1]
	v_exp_f32_e32 v144, v144
	v_exp_f32_e32 v145, v145
	v_exp_f32_e32 v146, v146
	v_exp_f32_e32 v147, v147
	v_pk_fma_f32 v[144:145], v[144:145], v[164:165], v[164:165] op_sel_hi:[1,0,0]
	v_pk_fma_f32 v[146:147], v[146:147], v[164:165], v[164:165] op_sel_hi:[1,0,0]
	v_rcp_f32_e32 v144, v144
	v_rcp_f32_e32 v145, v145
	v_rcp_f32_e32 v146, v146
	v_rcp_f32_e32 v147, v147
	v_pk_mul_f32 v[14:15], v[14:15], v[144:145]
	v_pk_mul_f32 v[10:11], v[10:11], v[146:147]
	v_cvt_pk_bf16_f32 v212, v14, v15
	v_cvt_pk_bf16_f32 v213, v10, v11
	v_pk_mul_f32 v[178:179], v[4:5], v[162:163] op_sel:[0,1] op_sel_hi:[1,1]
	v_pk_mul_f32 v[180:181], v[0:1], v[162:163] op_sel:[0,1] op_sel_hi:[1,1]
	v_exp_f32_e32 v178, v178
	v_exp_f32_e32 v179, v179
	v_exp_f32_e32 v180, v180
	v_exp_f32_e32 v181, v181
	v_pk_fma_f32 v[178:179], v[178:179], v[164:165], v[164:165] op_sel_hi:[1,0,0]
	v_pk_fma_f32 v[180:181], v[180:181], v[164:165], v[164:165] op_sel_hi:[1,0,0]
	v_rcp_f32_e32 v178, v178
	v_rcp_f32_e32 v179, v179
	v_rcp_f32_e32 v180, v180
	v_rcp_f32_e32 v181, v181
	v_pk_mul_f32 v[6:7], v[6:7], v[178:179]
	v_pk_mul_f32 v[2:3], v[2:3], v[180:181]
	v_cvt_pk_bf16_f32 v218, v6, v7
	v_cvt_pk_bf16_f32 v219, v2, v3
	v_lshl_add_u64 v[168:169], v[168:169], 0, s[64:65]
	v_permlane16_swap_b32_e32 v210, v212
	v_permlane16_swap_b32_e32 v211, v213
	global_store_dwordx4 v[168:169], v[210:213], off
	v_permlane16_swap_b32_e32 v216, v218
	v_permlane16_swap_b32_e32 v217, v219
	global_store_dwordx4 v[168:169], v[216:219], off offset:128
	s_cbranch_vccnz .LBB0_886
	s_andn2_b64 vcc, exec, s[4:5]
	s_cbranch_vccnz .LBB0_885
	s_barrier
	s_branch .LBB0_885
